# unit-start vmcnt waits sized for the stores really younger than the prefetched K/Q (8 behind a differential unit, 4 behind a window unit)
# speedup vs baseline: 1.0133x; 1.0015x over previous
; __global__ void __launch_bounds__(NWAVES * 64, 2) mk_fwd(Args args) {
;     ...
;             attn_body::bf16x8 qfr[4]; bool pref = false;
;             for (int v = vcu; v < 256; v += G) {
;                 for (int i = 0; i < 12; ++i) {
;                     long rowbase; int qb, t0, qc, kc, vc, oc; bool win; float s2, sink2; bf16* Ob;
;                     if (i < 8) {
;                         const int s = v & 7, bhv = (v >> 3) + 32 * (i >> 2), ii = i & 3, b = bhv >> 4, h = (bhv >> 2) & 3, c = (bhv >> 1) & 1, vh = bhv & 1;
;                         qb = (ii == 0) ? s : (ii == 1) ? 15 - s : (ii == 2) ? 16 + s : 31 - s; t0 = 0; win = false; rowbase = (long)b * SEQ;
;                         qc = 768 + h * 128 + c * 64; kc = 1280 + h * 128 + c * 64; vc = 1792 + h * 128 + vh * 64; oc = h * 128 + vh * 64; Ob = c ? OD1 : OD0;
;                         s2 = exp2f(-8.0f * (float)(9 + h) / 12.0f) * LOG2E; sink2 = -INFINITY;
;                     } else {
;                         const int ui = v * 4 + (i - 8), hq = (ui >> 5) & 7, b = ui >> 8; qb = ui & 31; t0 = qb > 0 ? 4 * qb - 2 : 0; win = true; rowbase = (long)b * SEQ;
;                         qc = hq * 64; kc = 512 + (hq >> 2) * 64; vc = 640 + (hq >> 2) * 64; oc = hq * 64; Ob = OA;
;                         s2 = exp2f(-8.0f * (float)(1 + hq) / 12.0f) * LOG2E; sink2 = ap->in[9][l * 8 + hq] * LOG2E;
;                     }
;                     int vn = v, in = i + 1; if (in == 12) { in = 0; vn = v + G; }
;                     if (vn >= 256) in = -1;
;                     attn_body::attn_unit<60>(rowbase, qb, t0, win, win ? nomax_swa : nomax_diff, (const attn_body::bf16*)QKV + qc, (const attn_body::bf16*)QKV + kc, (const attn_body::bf16*)QKV + vc, (attn_body::bf16*)Ob + oc, s2, sink2, (char*)lds,
;                         qfr, pref, (const attn_body::bf16*)QKV, vn, in);
;                     pref = in >= 0;
.LBB0_249:
	s_cmp_gt_u32 s85, 8
	s_cbranch_scc1 .Lmy_lh4
	s_waitcnt vmcnt(8)
	s_branch .Lmy_lhd
.Lmy_lh4:
	s_waitcnt vmcnt(4)
.Lmy_lhd:
	s_cmp_gt_u32 s85, 7
	v_mov_b64_e32 v[32:33], v[16:17]
	s_cselect_b64 s[62:63], -1, 0
	v_mov_b64_e32 v[30:31], v[14:15]
	v_mov_b64_e32 v[28:29], v[12:13]
	v_mov_b64_e32 v[26:27], v[10:11]
	v_mov_b64_e32 v[24:25], v[8:9]
	v_mov_b64_e32 v[22:23], v[6:7]
	v_mov_b64_e32 v[20:21], v[4:5]
	v_mov_b64_e32 v[18:19], v[2:3]
	s_mov_b64 s[44:45], -1
	s_and_b64 vcc, exec, s[62:63]
	s_cbranch_vccnz .LBB0_258
	s_and_b32 s48, s85, 3
	s_cmp_lt_i32 s48, 1
	s_cbranch_scc1 .LBB0_256
	s_cmp_lg_u32 s48, 1
	s_mov_b64 s[40:41], -1
	s_cbranch_scc0 .LBB0_253
	s_cmp_eq_u32 s48, 2
	v_readlane_b32 s2, v252, 15
	v_readlane_b32 s4, v252, 20
	s_cselect_b32 s2, s2, s4
	s_mov_b64 s[40:41], 0

; #define WAIT_BAR(N) asm volatile("s_waitcnt vmcnt(" #N ") lgkmcnt(0)\n\ts_barrier":::"memory")
;   #define DMA_K(t,slot) glds16(ksrc+(long)(t)*KVBLK*PIN,(unsigned)__builtin_amdgcn_readfirstlane(kdst+(slot)))
; template<int THRL> __device__ __forceinline__ void attn_unit(long rowbase,int qb,int t0,bool WIN,bool NOMAX,const bf16*Qc,const bf16*__restrict__ Kc,const bf16*__restrict__ Vc,bf16*Oc,float s2,float sink2,char*shm,
;     bf16x8 (&qr)[4],bool pref,const bf16*qkvb,int vn,int in_){
;     ...
;   if(!pref){ DMA_K(2,2*SLOTB);
;     WAIT_BAR(3); }
;   else { WAIT_BAR(5); }
.LBB0_264:
	s_cmp_gt_u32 s85, 8
	s_cbranch_scc1 .Lmy_wb7
	s_waitcnt vmcnt(10) lgkmcnt(0)
	s_branch .Lmy_wbd
.Lmy_wb7:
	s_waitcnt vmcnt(7) lgkmcnt(0)
.Lmy_wbd:
	s_barrier
